# mLSTM: normaliser-tile Cs write exec-masked to the 4 lanes that carry row 64
# baseline (speedup 1.0000x reference)
; #define LAS __attribute__((address_space(3)))
; __device__ __forceinline__ unsigned pk2(float lo, float hi) { unsigned r; asm("v_cvt_pk_bf16_f32 %0, %1, %2" : "=v"(r) : "v"(lo), "v"(hi)); return r; }
; #define MFMA16(a, b, c) __builtin_amdgcn_mfma_f32_16x16x32_bf16((a), (b), (c), 0, 0, 0)
; #define LDS_BARRIER() do { asm volatile("s_waitcnt lgkmcnt(0)" ::: "memory"); __builtin_amdgcn_s_barrier(); asm volatile("" ::: "memory"); } while (0)
; __device__ __forceinline__ void mlstm_item(const Args& a, LAS unsigned char* L, bool sample, int b, int hh, int sl, bool dry = false) {
;     ...
;         {
;             const int tt = wave & 1, vt = wave >> 1, t = tt * 16 + lr;
;             const bf16x8 Bs = *(const LAS bf16x8*)(L + L_SS + t * 80 + g * 16);
;             const f32x4 z4 = (f32x4){0.f, 0.f, 0.f, 0.f};
;             const bf16x8 Av = *(const LAS bf16x8*)(L + L_VT + (vt * 16 + lr) * 80 + g * 16);
;             bf16x8 Af[8], Bf[8];
; #pragma unroll
;             for (int kk = 0; kk < 8; ++kk) { Af[kk] = *(const LAS bf16x8*)(L + L_CS + (vt * 16 + lr) * 528 + kk * 64 + g * 16); Bf[kk] = *(const LAS bf16x8*)(L + L_QS + t * 528 + kk * 64 + g * 16); }
;             __builtin_amdgcn_sched_barrier(0);
;             f32x4 sM = MFMA16(Av, Bs, z4);
;             f32x4 cM = z4;
; #pragma unroll
;             for (int kk = 0; kk < 8; ++kk) cM = MFMA16(Af[kk], Bf[kk], cM);
;             const float d0 = __expf(m0c + GFM[c * 32 + t]), en = GEN[c * 32 + t];
;             const LAS float* NQ = (const LAS float*)(L + L_NQ);
;             const float nq = (NQ[t] + NQ[32 + t]) + d0 * (NQ[64 + t] + NQ[96 + t]);
;             const float inv = __builtin_amdgcn_rcpf(fmaxf(fabsf(nq), en));
;             float hv[4];
; #pragma unroll
;             for (int j = 0; j < 4; ++j) hv[j] = (sM[j] + d0 * cM[j]) * inv;
;             if (dry) *(u32x2*)((bf16_t*)a.out + (size_t)(rowbase + c * 32 + t) * 1024 + hh * 256 + sl * 64 + vt * 16 + g * 4) = (u32x2){pk2(hv[0], hv[1]), pk2(hv[2], hv[3])};
;             else *(u32x2*)(U + (size_t)(rowbase + c * 32 + t) * LDU + C_V + hh * 256 + sl * 64 + vt * 16 + g * 4) = (u32x2){pk2(hv[0], hv[1]), pk2(hv[2], hv[3])};
;         }
;         LDS_BARRIER();
;         WRITE_CS();
.Ldma_skip_loop:
	s_waitcnt lgkmcnt(0)
	v_mfma_f32_16x16x32_bf16 v[40:43], v[56:59], v[136:139], v[40:43]
	v_add_u32_e32 v58, v70, v99
	v_add_u32_e32 v57, v104, v222
	v_mfma_f32_16x16x32_bf16 v[32:35], v[116:119], v[120:123], v[32:35]
	v_mfma_f32_16x16x32_bf16 v[28:31], v[116:119], v[124:127], v[28:31]
	v_mfma_f32_16x16x32_bf16 v[24:27], v[116:119], v[128:131], v[24:27]
	v_mfma_f32_16x16x32_bf16 v[20:23], v[116:119], v[132:135], v[20:23]
	v_mfma_f32_16x16x32_bf16 v[16:19], v[116:119], v[136:139], v[16:19]
	ds_read_b128 v[116:119], v91 offset:46592
	ds_read_b128 v[120:123], v58 offset:33792
	ds_read_b128 v[124:127], v90 offset:49152
	ds_read_b128 v[132:135], v90 offset:49184
	ds_read_b128 v[140:143], v90 offset:49216
	ds_read_b128 v[148:151], v90 offset:49248
	ds_read_b128 v[156:159], v90 offset:49280
	ds_read_b128 v[164:167], v90 offset:49312
	ds_read_b128 v[172:175], v90 offset:49344
	ds_read_b128 v[182:185], v90 offset:49376
	s_waitcnt lgkmcnt(7)
	v_mfma_f32_16x16x32_bf16 v[124:127], v[124:127], v[190:193], 0
	v_add_u32_e32 v56, 0, v110
	v_add_u32_e32 v59, 0x16500, v56
	ds_read_b32 v59, v59
	s_waitcnt lgkmcnt(7)
	v_mfma_f32_16x16x32_bf16 v[124:127], v[132:135], v[194:197], v[124:127]
	v_add_u32_e32 v56, 0x1a500, v56
	ds_read2_b32 v[128:129], v89 offset1:32
	ds_read_b32 v56, v56
	ds_read2_b32 v[130:131], v89 offset0:64 offset1:96
	s_waitcnt lgkmcnt(9)
	v_mfma_f32_16x16x32_bf16 v[124:127], v[140:143], v[198:201], v[124:127]
	s_waitcnt lgkmcnt(3)
	v_add_f32_e32 v59, v115, v59
	v_mul_f32_e32 v59, 0x3fb8aa3b, v59
	v_exp_f32_e32 v59, v59
	v_mfma_f32_16x16x32_bf16 v[124:127], v[148:151], v[202:205], v[124:127]
	s_waitcnt lgkmcnt(2)
	v_mov_b32_e32 v132, v128
	s_waitcnt lgkmcnt(0)
	v_mov_b32_e32 v133, v130
	v_mov_b32_e32 v130, v129
	v_mfma_f32_16x16x32_bf16 v[124:127], v[156:159], v[206:209], v[124:127]
	v_add_f32_e64 v128, v132, v130
	v_add_f32_e64 v129, v133, v131
	v_max_f32_e32 v56, v56, v56
	v_fmac_f32_e32 v128, v59, v129
	v_mfma_f32_16x16x32_bf16 v[124:127], v[164:167], v[210:213], v[124:127]
	v_max_f32_e64 v56, |v128|, v56
	v_rcp_f32_e32 v56, v56
	s_lshl_b32 s42, s53, 1
	v_mfma_f32_16x16x32_bf16 v[124:127], v[172:175], v[214:217], v[124:127]
	s_mov_b32 s59, s43
	s_add_i32 s16, s16, 4
	s_add_u32 s70, s70, 0x70000
	v_mfma_f32_16x16x32_bf16 v[124:127], v[182:185], v[218:221], v[124:127]
	s_addc_u32 s71, s71, 0
	v_add_u32_e32 v114, 0x80, v114
	v_add_u32_e32 v110, 0x80, v110
	v_mfma_f32_16x16x32_bf16 v[116:119], v[120:123], v[116:119], 0
	v_cvt_pk_bf16_f32 v120, v48, v49
	v_cvt_pk_bf16_f32 v121, v50, v51
	s_cmp_eq_u32 s70, 0x1b90000
	v_add_u32_e32 v111, 0x80, v111
	v_cvt_pk_bf16_f32 v122, v44, v45
	s_nop 5
	v_fma_f32 v76, v124, v59, v116
	v_fma_f32 v115, v125, v59, v117
	v_fma_f32 v116, v126, v59, v118
	v_fmac_f32_e32 v119, v127, v59
	v_mul_f32_e32 v76, v76, v56
	v_mul_f32_e32 v115, v115, v56
	v_mul_f32_e32 v117, v116, v56
	v_mul_f32_e32 v56, v119, v56
	v_mov_b64_e32 v[118:119], s[28:29]
	v_mad_i64_i32 v[118:119], s[72:73], v109, s84, v[118:119]
	v_lshl_add_u64 v[118:119], v[118:119], 0, s[42:43]
	v_lshl_add_u64 v[118:119], v[118:119], 0, s[58:59]
	v_lshl_add_u64 v[118:119], s[56:57], 1, v[118:119]
	v_lshl_add_u64 v[118:119], v[118:119], 0, v[60:61]
	v_add_co_u32_e32 v118, vcc, s85, v118
	v_cvt_pk_bf16_f32 v116, v76, v115
	v_cvt_pk_bf16_f32 v117, v117, v56
	v_add_u32_e32 v59, 0xc000, v113
	s_nop 0
	v_addc_co_u32_e32 v119, vcc, 0, v119, vcc
	global_store_dwordx2 v[118:119], v[116:117], off
	v_cvt_pk_bf16_f32 v116, v36, v37
	v_cvt_pk_bf16_f32 v117, v38, v39
	s_waitcnt lgkmcnt(0)
	s_barrier
	v_cvt_pk_bf16_f32 v126, v32, v33
	v_cvt_pk_bf16_f32 v127, v34, v35
	ds_write2_b64 v59, v[116:117], v[126:127] offset1:2
	v_cvt_pk_bf16_f32 v116, v28, v29
	v_cvt_pk_bf16_f32 v117, v30, v31
	v_add_u32_e32 v76, 0xe000, v113
	v_cvt_pk_bf16_f32 v118, v52, v53
	v_cvt_pk_bf16_f32 v119, v54, v55
	ds_write2_b64 v76, v[118:119], v[116:117] offset0:32 offset1:34
	v_cvt_pk_bf16_f32 v116, v24, v25
	v_cvt_pk_bf16_f32 v117, v26, v27
	ds_write2_b64 v85, v[120:121], v[116:117] offset1:2
	v_cvt_pk_bf16_f32 v116, v20, v21
	v_cvt_pk_bf16_f32 v117, v22, v23
	v_add_u32_e32 v115, 0xe000, v86
	v_add_u32_e32 v109, 32, v109
	v_cvt_pk_bf16_f32 v123, v46, v47
	v_cvt_pk_bf16_f32 v124, v40, v41
	v_cvt_pk_bf16_f32 v125, v42, v43
	ds_write2_b64 v115, v[122:123], v[116:117] offset0:32 offset1:34
	v_cvt_pk_bf16_f32 v116, v16, v17
	v_cvt_pk_bf16_f32 v117, v18, v19
	s_mov_b32 exec_lo, 0x10001
	s_mov_b32 exec_hi, 0x10001
	ds_write2_b64 v67, v[124:125], v[116:117] offset0:32 offset1:34
	s_mov_b64 exec, -1
	s_cmp_eq_u32 s70, 0x1b90000
	s_cbranch_scc1 .LBB0_676
